# one-time s_sleep stagger of waves 4-7 at weight-conversion entry so load bursts and LDS/convert phases of the two wave halves interleave
# baseline (speedup 1.0000x reference)
; #define LAS __attribute__((address_space(3)))
; __device__ __forceinline__ void conv_matrix(const float* W, int K, int N, const float* gain, bf16_t* WT, int Kd, int mode, int row_off, LAS float* scr, int lane, int gw, int NGW) {
;     const int nblk = N / 32, items = nblk * (K / 64);
;     for (int it = gw; it < items; it += NGW) {
;         const int kb = it / nblk, nb = it % nblk, k0 = 64 * kb, n0 = 32 * nb;
;         float wv[32];
; #pragma unroll
;         for (int i = 0; i < 32; ++i) wv[i] = W[(size_t)(k0 + 2 * i + (lane >> 5)) * N + n0 + (lane & 31)];
; __device__ __forceinline__ void conv_ffn(const LAS Params* PL, int L, int which  , LAS float* scr, int lane, int gw, int NGW) {
;     const float* nrm = PL->in[which ? I_F2N : I_F1N] + (size_t)L * DM;
;     const float* wg = PL->in[which ? I_F2G : I_F1G] + (size_t)L * DM * FF;
;     const float* wu = PL->in[which ? I_F2U : I_F1U] + (size_t)L * DM * FF;
;     const float* wd = PL->in[which ? I_F2D : I_F1D] + (size_t)L * FF * DM;
;     bf16_t* gu = (bf16_t*)(PL->ws + (which ? (L ? WS_WGUC : WS_WGUB) : WS_WGUA)); bf16_t* dn = (bf16_t*)(PL->ws + (which ? (L ? WS_WDC : WS_WDB) : WS_WDA));
;     conv_matrix(wg, DM, FF, nrm, gu, DM, 1, 0, scr, lane, gw, NGW);
.Lconv_entry:
	s_ashr_i32 s5, s22, 6
	s_cmp_lt_u32 s5, 4
	s_cbranch_scc1 .Lno_stagger
	s_sleep 90
.Lno_stagger:
	s_lshl_b32 s4, s12, 3
	s_add_i32 s4, s5, s4
	s_lshl_b32 s5, s5, 14
	s_lshl_b32 s8, s10, 3
	s_add_i32 s5, s5, 0
	s_cmpk_gt_i32 s4, 0x15ff
	v_and_b32_e32 v1, 63, v54
	s_cbranch_scc1 .LBB0_101
	v_readlane_b32 s9, v254, 2
	s_waitcnt vmcnt(0) lgkmcnt(0)
	v_mov_b32_e32 v19, v0
	v_lshlrev_b32_e32 v11, 3, v1
	v_mov_b32_e32 v2, s9
	v_readlane_b32 s9, v254, 3
	v_lshrrev_b32_e32 v64, 3, v1
	v_lshrrev_b32_e32 v35, 5, v1
	v_mov_b32_e32 v3, s9
	v_readlane_b32 s9, v254, 4
	ds_read_b64 v[8:9], v2
	ds_read2_b64 v[2:5], v3 offset1:1
	v_mov_b32_e32 v6, s9
	v_readlane_b32 s9, v254, 5
	v_mov_b32_e32 v15, v0
	s_mov_b64 s[16:17], 0x1500000
	v_mov_b32_e32 v10, s9
	ds_read_b64 v[6:7], v6
	ds_read_b64 v[12:13], v10
	v_and_b32_e32 v10, 31, v54
	v_lshlrev_b32_e32 v18, 2, v10
	s_lshl_b32 s9, s4, 5
	s_lshl_b32 s22, s4, 6
	s_waitcnt lgkmcnt(0)
	v_lshl_add_u64 v[16:17], v[12:13], 0, v[18:19]
	v_and_b32_e32 v12, 56, v11
	v_mul_u32_u24_e32 v11, 0x84, v12
	v_lshlrev_b32_e32 v14, 1, v12
	v_lshlrev_b32_e32 v13, 2, v64
	v_lshl_add_u64 v[14:15], v[6:7], 0, v[14:15]
	v_add3_u32 v55, s5, v11, v13
	v_mul_u32_u24_e32 v11, 0x84, v35
	v_cmp_ne_u64_e64 s[40:41], 0, v[8:9]
	v_lshl_add_u64 v[14:15], v[14:15], 0, s[16:17]
	v_add3_u32 v56, s5, v18, v11
	v_or_b32_e32 v65, 8, v64
	v_or_b32_e32 v66, 16, v64
	v_or_b32_e32 v67, 24, v64
	s_lshl_b32 s12, s8, 5
	s_lshl_b32 s23, s8, 6
	s_mov_b32 s24, s22
	s_mov_b32 s25, s9
	s_mov_b32 s27, s4
	s_cmp_lg_u32 s58, 0
	s_cbranch_scc1 .Lskip_a1
	s_branch .LBB0_81
